# EpiResid first half: residual fragment loads as 16-byte loads + v_permlane16_swap
# speedup vs baseline: 1.0205x; 1.0031x over previous
; __device__ __forceinline__ unsigned cvt_pk_bf16(float lo, float hi) { unsigned r; asm volatile("v_cvt_pk_bf16_f32 %0, %1, %2" : "=v"(r) : "v"(lo), "v"(hi)); return r; }
;     __device__ __forceinline__ void operator()(f32x4 (&acc)[2][2][4][2], const Unit& u, int wr, int wc, int fr, int fq) const {
;         const int col0 = u.pn * BM + wc * 32 + 4 * fq;
; #pragma unroll
;         for (int ai = 0; ai < 2; ++ai) {
;             unsigned long long old[4][2][2];
; #pragma unroll
;             for (int m = 0; m < 4; ++m) { const size_t off = (size_t)(u.pm * BM + ai * HALF + wr * 64 + m * 16 + fr) * ldc + col0;
; #pragma unroll
;                 for (int bj = 0; bj < 2; ++bj)
; #pragma unroll
;                     for (int n = 0; n < 2; ++n) old[m][bj][n] = *(const unsigned long long*)(xb + off + bj * HALF + n * 16); }
; #pragma unroll
;             for (int m = 0; m < 4; ++m) { const int row = u.pm * BM + ai * HALF + wr * 64 + m * 16 + fr; const size_t off = (size_t)row * ldc + col0; float sq = 0.f;
; #pragma unroll
;                 for (int bj = 0; bj < 2; ++bj)
; #pragma unroll
;                     for (int n = 0; n < 2; ++n) { const unsigned long long b = old[m][bj][n];
;                         const unsigned blo = (unsigned)b, bhi = (unsigned)(b >> 32);
;                         f32x4 v; v[0] = __builtin_bit_cast(float, blo << 16); v[1] = __builtin_bit_cast(float, blo & 0xffff0000u); v[2] = __builtin_bit_cast(float, bhi << 16); v[3] = __builtin_bit_cast(float, bhi & 0xffff0000u);
;                         v = v + acc[ai][bj][m][n];
;                         sq += (v[0] * v[0] + v[1] * v[1]) + (v[2] * v[2] + v[3] * v[3]);
;                         *(unsigned long long*)(xb + off + bj * HALF + n * 16) = (unsigned long long)cvt_pk_bf16(v[0], v[1]) | ((unsigned long long)cvt_pk_bf16(v[2], v[3]) << 32); }
;                 sq += __shfl_xor(sq, 16); sq += __shfl_xor(sq, 32);
;                 if (fq == 0) ssp[(size_t)row * 16 + 4 * u.pn + wc] = sq; }
.LBB0_1039:
	v_bfe_u32 v200, v229, 4, 1
	v_mul_u32_u24_e32 v200, 24, v200
	v_mov_b32_e32 v201, 0
	v_lshl_or_b32 v136, s12, 8, v174
	v_lshl_add_u32 v140, s13, 8, v172
	v_ashrrev_i32_e32 v137, 31, v136
	v_lshlrev_b64 v[176:177], 1, v[136:137]
	v_ashrrev_i32_e32 v141, 31, v140
	v_lshl_add_u64 v[138:139], s[42:43], 0, v[176:177]
	v_lshlrev_b64 v[178:179], 11, v[140:141]
	v_lshl_add_u64 v[142:143], v[138:139], 0, v[178:179]
	v_lshl_add_u64 v[142:143], v[142:143], 0, v[200:201]
	global_load_dwordx4 v[148:151], v[142:143], off
	global_load_dwordx4 v[152:155], v[142:143], off offset:256
	v_or_b32_e32 v160, 16, v140
	v_ashrrev_i32_e32 v161, 31, v160
	v_lshlrev_b64 v[142:143], 11, v[160:161]
	v_or_b32_e32 v146, 32, v140
	v_lshl_add_u64 v[142:143], v[138:139], 0, v[142:143]
	v_ashrrev_i32_e32 v147, 31, v146
	v_lshl_add_u64 v[142:143], v[142:143], 0, v[200:201]
	global_load_dwordx4 v[156:159], v[142:143], off
	global_load_dwordx4 v[162:165], v[142:143], off offset:256
	v_lshlrev_b64 v[142:143], 11, v[146:147]
	v_lshl_add_u64 v[142:143], v[138:139], 0, v[142:143]
	v_lshl_add_u64 v[142:143], v[142:143], 0, v[200:201]
	global_load_dwordx4 v[166:169], v[142:143], off
	global_load_dwordx4 v[180:183], v[142:143], off offset:256
	v_or_b32_e32 v142, 48, v140
	v_ashrrev_i32_e32 v143, 31, v142
	v_lshlrev_b64 v[144:145], 11, v[142:143]
	v_lshl_add_u64 v[144:145], v[138:139], 0, v[144:145]
	v_lshl_add_u64 v[144:145], v[144:145], 0, v[200:201]
	global_load_dwordx4 v[202:205], v[144:145], off
	s_nop 0
	global_load_dwordx4 v[206:209], v[144:145], off offset:256
	s_lshl_b32 s78, s12, 2
	s_ashr_i32 s79, s78, 31
	s_waitcnt vmcnt(0)
	v_permlane16_swap_b32_e32 v148, v150
	v_permlane16_swap_b32_e32 v149, v151
	v_permlane16_swap_b32_e32 v152, v154
	v_permlane16_swap_b32_e32 v153, v155
	v_permlane16_swap_b32_e32 v156, v158
	v_permlane16_swap_b32_e32 v157, v159
	v_permlane16_swap_b32_e32 v162, v164
	v_permlane16_swap_b32_e32 v163, v165
	v_permlane16_swap_b32_e32 v166, v168
	v_permlane16_swap_b32_e32 v167, v169
	v_permlane16_swap_b32_e32 v180, v182
	v_permlane16_swap_b32_e32 v181, v183
	v_permlane16_swap_b32_e32 v202, v204
	v_permlane16_swap_b32_e32 v203, v205
	v_permlane16_swap_b32_e32 v206, v208
	v_permlane16_swap_b32_e32 v207, v209
	v_mov_b32_e32 v184, v152
	v_mov_b32_e32 v185, v153
	v_mov_b32_e32 v188, v154
	v_mov_b32_e32 v189, v155
	v_mov_b32_e32 v170, v156
	v_mov_b32_e32 v171, v157
	v_mov_b32_e32 v154, v180
	v_mov_b32_e32 v180, v148
	v_mov_b32_e32 v155, v181
	v_mov_b32_e32 v181, v149
	v_mov_b32_e32 v156, v202
	v_mov_b32_e32 v157, v203
	v_mov_b32_e32 v152, v204
	v_mov_b32_e32 v153, v205
	v_mov_b32_e32 v148, v206
	v_mov_b32_e32 v149, v207
	v_mov_b32_e32 v144, v208
	v_mov_b32_e32 v145, v209
	v_mov_b32_e32 v199, v182
	v_mov_b32_e32 v182, v150
	v_mov_b32_e32 v150, v199
	v_mov_b32_e32 v198, v183
	v_mov_b32_e32 v183, v151
	v_mov_b32_e32 v151, v198
	v_mov_b32_e32 v197, v168
	v_mov_b32_e32 v168, v158
	v_mov_b32_e32 v158, v197
	v_mov_b32_e32 v196, v169
	v_mov_b32_e32 v169, v159
	v_mov_b32_e32 v159, v196
	v_mov_b32_e32 v195, v166
	v_mov_b32_e32 v166, v162
	v_mov_b32_e32 v162, v195
	v_mov_b32_e32 v194, v167
	v_mov_b32_e32 v167, v163
	v_mov_b32_e32 v163, v194
	s_mov_b32 s100, 1
	v_lshlrev_b32_e32 v190, 16, v180
	v_and_b32_e32 v191, 0xffff0000, v180
	v_lshlrev_b32_e32 v180, 16, v181
	v_and_b32_e32 v181, 0xffff0000, v181
	v_pk_add_f32 v[128:129], v[128:129], v[180:181]
	v_pk_add_f32 v[126:127], v[126:127], v[190:191]
	v_mul_f32_e32 v181, v129, v129
	v_mul_f32_e32 v180, v127, v127
	v_fmac_f32_e32 v180, v126, v126
	v_fmac_f32_e32 v181, v128, v128
	v_cvt_pk_bf16_f32 v126, v126, v127
	v_cvt_pk_bf16_f32 v127, v128, v129
	v_lshl_add_u64 v[128:129], s[42:43], 0, v[178:179]
	v_lshl_add_u64 v[128:129], v[128:129], 0, v[176:177]
	v_lshl_add_u64 v[128:129], v[128:129], 0, v[200:201]
	v_mov_b32_e32 v192, v126
	v_mov_b32_e32 v193, v127
	v_lshlrev_b32_e32 v126, 16, v182
	v_and_b32_e32 v127, 0xffff0000, v182
	v_pk_add_f32 v[122:123], v[122:123], v[126:127]
	v_lshlrev_b32_e32 v176, 16, v183
	v_and_b32_e32 v177, 0xffff0000, v183
	v_mul_f32_e32 v126, v123, v123
	v_pk_add_f32 v[124:125], v[124:125], v[176:177]
	v_fmac_f32_e32 v126, v122, v122
	v_cvt_pk_bf16_f32 v122, v122, v123
	v_cvt_pk_bf16_f32 v123, v124, v125
	v_mul_f32_e32 v127, v125, v125
	v_mov_b32_e32 v194, v122
	v_mov_b32_e32 v195, v123
	s_nop 1
	v_permlane16_swap_b32_e32 v192, v194
	v_permlane16_swap_b32_e32 v193, v195
	global_store_dwordx4 v[128:129], v[192:195], off
	v_lshlrev_b32_e32 v122, 16, v184
	v_and_b32_e32 v123, 0xffff0000, v184
	v_fmac_f32_e32 v127, v124, v124
	v_lshlrev_b32_e32 v124, 16, v185
	v_and_b32_e32 v125, 0xffff0000, v185
	v_pk_add_f32 v[118:119], v[118:119], v[122:123]
	v_pk_add_f32 v[120:121], v[120:121], v[124:125]
	v_mul_f32_e32 v122, v119, v119
	v_fmac_f32_e32 v122, v118, v118
	v_mul_f32_e32 v123, v121, v121
	v_cvt_pk_bf16_f32 v118, v118, v119
	v_cvt_pk_bf16_f32 v119, v120, v121
	v_fmac_f32_e32 v123, v120, v120
	v_mov_b32_e32 v196, v118
	v_mov_b32_e32 v197, v119
	v_lshlrev_b32_e32 v118, 16, v188
	v_and_b32_e32 v119, 0xffff0000, v188
	v_lshlrev_b32_e32 v120, 16, v189
	v_and_b32_e32 v121, 0xffff0000, v189
	v_pk_add_f32 v[116:117], v[116:117], v[120:121]
	v_pk_add_f32 v[118:119], v[114:115], v[118:119]
	v_add_f32_e32 v180, v180, v181
	v_add_f32_e32 v126, v126, v127
	v_mul_f32_e32 v114, v119, v119
	v_mul_f32_e32 v115, v117, v117
	v_add_f32_e32 v126, v180, v126
	v_add_f32_e32 v122, v122, v123
	v_fmac_f32_e32 v114, v118, v118
	v_fmac_f32_e32 v115, v116, v116
	v_add_f32_e32 v122, v126, v122
	v_add_f32_e32 v114, v114, v115
	v_cvt_pk_bf16_f32 v118, v118, v119
	v_cvt_pk_bf16_f32 v119, v116, v117
	v_and_b32_e32 v116, 64, v229
	v_add_f32_e32 v115, v122, v114
	v_xor_b32_e32 v114, 16, v229
	v_add_u32_e32 v117, 64, v116
	v_cmp_lt_i32_e32 vcc, v114, v117
	v_mov_b32_e32 v198, v118
	v_mov_b32_e32 v199, v119
	s_nop 1
	v_permlane16_swap_b32_e32 v196, v198
	v_permlane16_swap_b32_e32 v197, v199
	global_store_dwordx4 v[128:129], v[196:199], off offset:256
	s_nop 0
	v_cndmask_b32_e32 v114, v229, v114, vcc
	v_lshlrev_b32_e32 v114, 2, v114
	v_mov_b32_e32 v116, v115
	s_nop 1
	v_permlane16_swap_b32_e32 v116, v115
	s_waitcnt lgkmcnt(0)
	v_add_f32_e32 v116, v115, v116
	v_xor_b32_e32 v115, 32, v229
	v_cmp_lt_i32_e32 vcc, v115, v117
	s_nop 1
	v_cndmask_b32_e32 v115, v229, v115, vcc
	v_lshlrev_b32_e32 v115, 2, v115
	ds_bpermute_b32 v117, v115, v116
	s_and_saveexec_b64 s[80:81], s[6:7]
	s_cbranch_execz .LBB0_1041
	v_readlane_b32 s12, v253, 40
	v_lshlrev_b64 v[118:119], 6, v[140:141]
	v_readlane_b32 s13, v253, 41
	s_lshl_b32 s64, s90, 2
	s_waitcnt lgkmcnt(0)
	v_add_f32_e32 v116, v116, v117
	v_lshl_add_u64 v[118:119], s[12:13], 0, v[118:119]
	v_lshl_add_u64 v[118:119], s[78:79], 2, v[118:119]
	v_lshl_add_u64 v[118:119], v[118:119], 0, s[64:65]
	global_store_dword v[118:119], v116, off

; __device__ __forceinline__ unsigned cvt_pk_bf16(float lo, float hi) { unsigned r; asm volatile("v_cvt_pk_bf16_f32 %0, %1, %2" : "=v"(r) : "v"(lo), "v"(hi)); return r; }
;     __device__ __forceinline__ void operator()(f32x4 (&acc)[2][2][4][2], const Unit& u, int wr, int wc, int fr, int fq) const {
;         const int col0 = u.pn * BM + wc * 32 + 4 * fq;
; #pragma unroll
;         for (int ai = 0; ai < 2; ++ai) {
;             unsigned long long old[4][2][2];
; #pragma unroll
;             for (int m = 0; m < 4; ++m) { const size_t off = (size_t)(u.pm * BM + ai * HALF + wr * 64 + m * 16 + fr) * ldc + col0;
; #pragma unroll
;                 for (int bj = 0; bj < 2; ++bj)
; #pragma unroll
;                     for (int n = 0; n < 2; ++n) old[m][bj][n] = *(const unsigned long long*)(xb + off + bj * HALF + n * 16); }
; #pragma unroll
;             for (int m = 0; m < 4; ++m) { const int row = u.pm * BM + ai * HALF + wr * 64 + m * 16 + fr; const size_t off = (size_t)row * ldc + col0; float sq = 0.f;
; #pragma unroll
;                 for (int bj = 0; bj < 2; ++bj)
; #pragma unroll
;                     for (int n = 0; n < 2; ++n) { const unsigned long long b = old[m][bj][n];
;                         const unsigned blo = (unsigned)b, bhi = (unsigned)(b >> 32);
;                         f32x4 v; v[0] = __builtin_bit_cast(float, blo << 16); v[1] = __builtin_bit_cast(float, blo & 0xffff0000u); v[2] = __builtin_bit_cast(float, bhi << 16); v[3] = __builtin_bit_cast(float, bhi & 0xffff0000u);
;                         v = v + acc[ai][bj][m][n];
;                         sq += (v[0] * v[0] + v[1] * v[1]) + (v[2] * v[2] + v[3] * v[3]);
;                         *(unsigned long long*)(xb + off + bj * HALF + n * 16) = (unsigned long long)cvt_pk_bf16(v[0], v[1]) | ((unsigned long long)cvt_pk_bf16(v[2], v[3]) << 32); }
;                 sq += __shfl_xor(sq, 16); sq += __shfl_xor(sq, 32);
;                 if (fq == 0) ssp[(size_t)row * 16 + 4 * u.pn + wc] = sq; }
.LBB0_1266:
	v_bfe_u32 v200, v229, 4, 1
	v_mul_u32_u24_e32 v200, 24, v200
	v_mov_b32_e32 v201, 0
	v_lshl_or_b32 v136, s12, 8, v174
	v_lshl_add_u32 v140, s13, 8, v172
	v_ashrrev_i32_e32 v137, 31, v136
	v_lshlrev_b64 v[176:177], 1, v[136:137]
	v_ashrrev_i32_e32 v141, 31, v140
	v_lshl_add_u64 v[138:139], s[42:43], 0, v[176:177]
	v_lshlrev_b64 v[178:179], 11, v[140:141]
	v_lshl_add_u64 v[142:143], v[138:139], 0, v[178:179]
	v_lshl_add_u64 v[142:143], v[142:143], 0, v[200:201]
	global_load_dwordx4 v[148:151], v[142:143], off
	global_load_dwordx4 v[152:155], v[142:143], off offset:256
	v_or_b32_e32 v160, 16, v140
	v_ashrrev_i32_e32 v161, 31, v160
	v_lshlrev_b64 v[142:143], 11, v[160:161]
	v_or_b32_e32 v146, 32, v140
	v_lshl_add_u64 v[142:143], v[138:139], 0, v[142:143]
	v_ashrrev_i32_e32 v147, 31, v146
	v_lshl_add_u64 v[142:143], v[142:143], 0, v[200:201]
	global_load_dwordx4 v[156:159], v[142:143], off
	global_load_dwordx4 v[162:165], v[142:143], off offset:256
	v_lshlrev_b64 v[142:143], 11, v[146:147]
	v_lshl_add_u64 v[142:143], v[138:139], 0, v[142:143]
	v_lshl_add_u64 v[142:143], v[142:143], 0, v[200:201]
	global_load_dwordx4 v[166:169], v[142:143], off
	global_load_dwordx4 v[180:183], v[142:143], off offset:256
	v_or_b32_e32 v142, 48, v140
	v_ashrrev_i32_e32 v143, 31, v142
	v_lshlrev_b64 v[144:145], 11, v[142:143]
	v_lshl_add_u64 v[144:145], v[138:139], 0, v[144:145]
	v_lshl_add_u64 v[144:145], v[144:145], 0, v[200:201]
	global_load_dwordx4 v[202:205], v[144:145], off
	s_nop 0
	global_load_dwordx4 v[206:209], v[144:145], off offset:256
	s_lshl_b32 s76, s12, 2
	s_ashr_i32 s77, s76, 31
	s_waitcnt vmcnt(0)
	v_permlane16_swap_b32_e32 v148, v150
	v_permlane16_swap_b32_e32 v149, v151
	v_permlane16_swap_b32_e32 v152, v154
	v_permlane16_swap_b32_e32 v153, v155
	v_permlane16_swap_b32_e32 v156, v158
	v_permlane16_swap_b32_e32 v157, v159
	v_permlane16_swap_b32_e32 v162, v164
	v_permlane16_swap_b32_e32 v163, v165
	v_permlane16_swap_b32_e32 v166, v168
	v_permlane16_swap_b32_e32 v167, v169
	v_permlane16_swap_b32_e32 v180, v182
	v_permlane16_swap_b32_e32 v181, v183
	v_permlane16_swap_b32_e32 v202, v204
	v_permlane16_swap_b32_e32 v203, v205
	v_permlane16_swap_b32_e32 v206, v208
	v_permlane16_swap_b32_e32 v207, v209
	v_mov_b32_e32 v184, v152
	v_mov_b32_e32 v185, v153
	v_mov_b32_e32 v188, v154
	v_mov_b32_e32 v189, v155
	v_mov_b32_e32 v170, v156
	v_mov_b32_e32 v171, v157
	v_mov_b32_e32 v154, v180
	v_mov_b32_e32 v180, v148
	v_mov_b32_e32 v155, v181
	v_mov_b32_e32 v181, v149
	v_mov_b32_e32 v156, v202
	v_mov_b32_e32 v157, v203
	v_mov_b32_e32 v152, v204
	v_mov_b32_e32 v153, v205
	v_mov_b32_e32 v148, v206
	v_mov_b32_e32 v149, v207
	v_mov_b32_e32 v144, v208
	v_mov_b32_e32 v145, v209
	v_mov_b32_e32 v199, v182
	v_mov_b32_e32 v182, v150
	v_mov_b32_e32 v150, v199
	v_mov_b32_e32 v198, v183
	v_mov_b32_e32 v183, v151
	v_mov_b32_e32 v151, v198
	v_mov_b32_e32 v197, v168
	v_mov_b32_e32 v168, v158
	v_mov_b32_e32 v158, v197
	v_mov_b32_e32 v196, v169
	v_mov_b32_e32 v169, v159
	v_mov_b32_e32 v159, v196
	v_mov_b32_e32 v195, v166
	v_mov_b32_e32 v166, v162
	v_mov_b32_e32 v162, v195
	v_mov_b32_e32 v194, v167
	v_mov_b32_e32 v167, v163
	v_mov_b32_e32 v163, v194
	s_mov_b32 s100, 1
	v_lshlrev_b32_e32 v190, 16, v180
	v_and_b32_e32 v191, 0xffff0000, v180
	v_lshlrev_b32_e32 v180, 16, v181
	v_and_b32_e32 v181, 0xffff0000, v181
	v_pk_add_f32 v[128:129], v[128:129], v[180:181]
	v_pk_add_f32 v[126:127], v[126:127], v[190:191]
	v_mul_f32_e32 v181, v129, v129
	v_mul_f32_e32 v180, v127, v127
	v_fmac_f32_e32 v180, v126, v126
	v_fmac_f32_e32 v181, v128, v128
	v_cvt_pk_bf16_f32 v126, v126, v127
	v_cvt_pk_bf16_f32 v127, v128, v129
	v_lshl_add_u64 v[128:129], s[42:43], 0, v[178:179]
	v_lshl_add_u64 v[128:129], v[128:129], 0, v[176:177]
	v_lshl_add_u64 v[128:129], v[128:129], 0, v[200:201]
	v_mov_b32_e32 v192, v126
	v_mov_b32_e32 v193, v127
	v_lshlrev_b32_e32 v126, 16, v182
	v_and_b32_e32 v127, 0xffff0000, v182
	v_pk_add_f32 v[122:123], v[122:123], v[126:127]
	v_lshlrev_b32_e32 v176, 16, v183
	v_and_b32_e32 v177, 0xffff0000, v183
	v_mul_f32_e32 v126, v123, v123
	v_pk_add_f32 v[124:125], v[124:125], v[176:177]
	v_fmac_f32_e32 v126, v122, v122
	v_cvt_pk_bf16_f32 v122, v122, v123
	v_cvt_pk_bf16_f32 v123, v124, v125
	v_mul_f32_e32 v127, v125, v125
	v_mov_b32_e32 v194, v122
	v_mov_b32_e32 v195, v123
	s_nop 1
	v_permlane16_swap_b32_e32 v192, v194
	v_permlane16_swap_b32_e32 v193, v195
	global_store_dwordx4 v[128:129], v[192:195], off
	v_lshlrev_b32_e32 v122, 16, v184
	v_and_b32_e32 v123, 0xffff0000, v184
	v_fmac_f32_e32 v127, v124, v124
	v_lshlrev_b32_e32 v124, 16, v185
	v_and_b32_e32 v125, 0xffff0000, v185
	v_pk_add_f32 v[118:119], v[118:119], v[122:123]
	v_pk_add_f32 v[120:121], v[120:121], v[124:125]
	v_mul_f32_e32 v122, v119, v119
	v_fmac_f32_e32 v122, v118, v118
	v_mul_f32_e32 v123, v121, v121
	v_cvt_pk_bf16_f32 v118, v118, v119
	v_cvt_pk_bf16_f32 v119, v120, v121
	v_fmac_f32_e32 v123, v120, v120
	v_mov_b32_e32 v196, v118
	v_mov_b32_e32 v197, v119
	v_lshlrev_b32_e32 v118, 16, v188
	v_and_b32_e32 v119, 0xffff0000, v188
	v_lshlrev_b32_e32 v120, 16, v189
	v_and_b32_e32 v121, 0xffff0000, v189
	v_pk_add_f32 v[116:117], v[116:117], v[120:121]
	v_pk_add_f32 v[118:119], v[114:115], v[118:119]
	v_add_f32_e32 v180, v180, v181
	v_add_f32_e32 v126, v126, v127
	v_mul_f32_e32 v114, v119, v119
	v_mul_f32_e32 v115, v117, v117
	v_add_f32_e32 v126, v180, v126
	v_add_f32_e32 v122, v122, v123
	v_fmac_f32_e32 v114, v118, v118
	v_fmac_f32_e32 v115, v116, v116
	v_add_f32_e32 v122, v126, v122
	v_add_f32_e32 v114, v114, v115
	v_cvt_pk_bf16_f32 v118, v118, v119
	v_cvt_pk_bf16_f32 v119, v116, v117
	v_and_b32_e32 v116, 64, v229
	v_add_f32_e32 v115, v122, v114
	v_xor_b32_e32 v114, 16, v229
	v_add_u32_e32 v117, 64, v116
	v_cmp_lt_i32_e32 vcc, v114, v117
	v_mov_b32_e32 v198, v118
	v_mov_b32_e32 v199, v119
	s_nop 1
	v_permlane16_swap_b32_e32 v196, v198
	v_permlane16_swap_b32_e32 v197, v199
	global_store_dwordx4 v[128:129], v[196:199], off offset:256
	s_nop 0
	v_cndmask_b32_e32 v114, v229, v114, vcc
	v_lshlrev_b32_e32 v114, 2, v114
	v_mov_b32_e32 v116, v115
	s_nop 1
	v_permlane16_swap_b32_e32 v116, v115
	s_waitcnt lgkmcnt(0)
	v_add_f32_e32 v116, v115, v116
	v_xor_b32_e32 v115, 32, v229
	v_cmp_lt_i32_e32 vcc, v115, v117
	s_nop 1
	v_cndmask_b32_e32 v115, v229, v115, vcc
	v_lshlrev_b32_e32 v115, 2, v115
	ds_bpermute_b32 v117, v115, v116
	s_and_saveexec_b64 s[78:79], s[6:7]
	s_cbranch_execz .LBB0_1268
	v_lshlrev_b64 v[118:119], 6, v[140:141]
	v_lshl_add_u64 v[118:119], s[14:15], 0, v[118:119]
	v_lshl_add_u64 v[118:119], s[76:77], 2, v[118:119]
	s_lshl_b32 s64, s86, 2
	v_lshl_add_u64 v[118:119], v[118:119], 0, s[64:65]
	s_waitcnt lgkmcnt(0)
	v_add_f32_e32 v116, v116, v117
	global_store_dword v[118:119], v116, off

; __device__ __forceinline__ unsigned cvt_pk_bf16(float lo, float hi) { unsigned r; asm volatile("v_cvt_pk_bf16_f32 %0, %1, %2" : "=v"(r) : "v"(lo), "v"(hi)); return r; }
;     __device__ __forceinline__ void operator()(f32x4 (&acc)[2][2][4][2], const Unit& u, int wr, int wc, int fr, int fq) const {
;         const int col0 = u.pn * BM + wc * 32 + 4 * fq;
; #pragma unroll
;         for (int ai = 0; ai < 2; ++ai) {
;             unsigned long long old[4][2][2];
; #pragma unroll
;             for (int m = 0; m < 4; ++m) { const size_t off = (size_t)(u.pm * BM + ai * HALF + wr * 64 + m * 16 + fr) * ldc + col0;
; #pragma unroll
;                 for (int bj = 0; bj < 2; ++bj)
; #pragma unroll
;                     for (int n = 0; n < 2; ++n) old[m][bj][n] = *(const unsigned long long*)(xb + off + bj * HALF + n * 16); }
; #pragma unroll
;             for (int m = 0; m < 4; ++m) { const int row = u.pm * BM + ai * HALF + wr * 64 + m * 16 + fr; const size_t off = (size_t)row * ldc + col0; float sq = 0.f;
; #pragma unroll
;                 for (int bj = 0; bj < 2; ++bj)
; #pragma unroll
;                     for (int n = 0; n < 2; ++n) { const unsigned long long b = old[m][bj][n];
;                         const unsigned blo = (unsigned)b, bhi = (unsigned)(b >> 32);
;                         f32x4 v; v[0] = __builtin_bit_cast(float, blo << 16); v[1] = __builtin_bit_cast(float, blo & 0xffff0000u); v[2] = __builtin_bit_cast(float, bhi << 16); v[3] = __builtin_bit_cast(float, bhi & 0xffff0000u);
;                         v = v + acc[ai][bj][m][n];
;                         sq += (v[0] * v[0] + v[1] * v[1]) + (v[2] * v[2] + v[3] * v[3]);
;                         *(unsigned long long*)(xb + off + bj * HALF + n * 16) = (unsigned long long)cvt_pk_bf16(v[0], v[1]) | ((unsigned long long)cvt_pk_bf16(v[2], v[3]) << 32); }
;                 sq += __shfl_xor(sq, 16); sq += __shfl_xor(sq, 32);
;                 if (fq == 0) ssp[(size_t)row * 16 + 4 * u.pn + wc] = sq; }
.LBB0_1515:
	v_bfe_u32 v200, v229, 4, 1
	v_mul_u32_u24_e32 v200, 24, v200
	v_mov_b32_e32 v201, 0
	v_lshl_or_b32 v136, s12, 8, v174
	v_lshl_add_u32 v140, s13, 8, v172
	v_ashrrev_i32_e32 v137, 31, v136
	v_lshlrev_b64 v[176:177], 1, v[136:137]
	v_ashrrev_i32_e32 v141, 31, v140
	v_lshl_add_u64 v[138:139], s[42:43], 0, v[176:177]
	v_lshlrev_b64 v[178:179], 11, v[140:141]
	v_lshl_add_u64 v[142:143], v[138:139], 0, v[178:179]
	v_lshl_add_u64 v[142:143], v[142:143], 0, v[200:201]
	global_load_dwordx4 v[148:151], v[142:143], off
	global_load_dwordx4 v[152:155], v[142:143], off offset:256
	v_or_b32_e32 v160, 16, v140
	v_ashrrev_i32_e32 v161, 31, v160
	v_lshlrev_b64 v[142:143], 11, v[160:161]
	v_or_b32_e32 v146, 32, v140
	v_lshl_add_u64 v[142:143], v[138:139], 0, v[142:143]
	v_ashrrev_i32_e32 v147, 31, v146
	v_lshl_add_u64 v[142:143], v[142:143], 0, v[200:201]
	global_load_dwordx4 v[156:159], v[142:143], off
	global_load_dwordx4 v[162:165], v[142:143], off offset:256
	v_lshlrev_b64 v[142:143], 11, v[146:147]
	v_lshl_add_u64 v[142:143], v[138:139], 0, v[142:143]
	v_lshl_add_u64 v[142:143], v[142:143], 0, v[200:201]
	global_load_dwordx4 v[166:169], v[142:143], off
	global_load_dwordx4 v[180:183], v[142:143], off offset:256
	v_or_b32_e32 v142, 48, v140
	v_ashrrev_i32_e32 v143, 31, v142
	v_lshlrev_b64 v[144:145], 11, v[142:143]
	v_lshl_add_u64 v[144:145], v[138:139], 0, v[144:145]
	v_lshl_add_u64 v[144:145], v[144:145], 0, v[200:201]
	global_load_dwordx4 v[202:205], v[144:145], off
	s_nop 0
	global_load_dwordx4 v[206:209], v[144:145], off offset:256
	s_lshl_b32 s72, s12, 2
	s_ashr_i32 s73, s72, 31
	s_waitcnt vmcnt(0)
	v_permlane16_swap_b32_e32 v148, v150
	v_permlane16_swap_b32_e32 v149, v151
	v_permlane16_swap_b32_e32 v152, v154
	v_permlane16_swap_b32_e32 v153, v155
	v_permlane16_swap_b32_e32 v156, v158
	v_permlane16_swap_b32_e32 v157, v159
	v_permlane16_swap_b32_e32 v162, v164
	v_permlane16_swap_b32_e32 v163, v165
	v_permlane16_swap_b32_e32 v166, v168
	v_permlane16_swap_b32_e32 v167, v169
	v_permlane16_swap_b32_e32 v180, v182
	v_permlane16_swap_b32_e32 v181, v183
	v_permlane16_swap_b32_e32 v202, v204
	v_permlane16_swap_b32_e32 v203, v205
	v_permlane16_swap_b32_e32 v206, v208
	v_permlane16_swap_b32_e32 v207, v209
	v_mov_b32_e32 v184, v152
	v_mov_b32_e32 v185, v153
	v_mov_b32_e32 v188, v154
	v_mov_b32_e32 v189, v155
	v_mov_b32_e32 v170, v156
	v_mov_b32_e32 v171, v157
	v_mov_b32_e32 v154, v180
	v_mov_b32_e32 v180, v148
	v_mov_b32_e32 v155, v181
	v_mov_b32_e32 v181, v149
	v_mov_b32_e32 v156, v202
	v_mov_b32_e32 v157, v203
	v_mov_b32_e32 v152, v204
	v_mov_b32_e32 v153, v205
	v_mov_b32_e32 v148, v206
	v_mov_b32_e32 v149, v207
	v_mov_b32_e32 v144, v208
	v_mov_b32_e32 v145, v209
	v_mov_b32_e32 v199, v182
	v_mov_b32_e32 v182, v150
	v_mov_b32_e32 v150, v199
	v_mov_b32_e32 v198, v183
	v_mov_b32_e32 v183, v151
	v_mov_b32_e32 v151, v198
	v_mov_b32_e32 v197, v168
	v_mov_b32_e32 v168, v158
	v_mov_b32_e32 v158, v197
	v_mov_b32_e32 v196, v169
	v_mov_b32_e32 v169, v159
	v_mov_b32_e32 v159, v196
	v_mov_b32_e32 v195, v166
	v_mov_b32_e32 v166, v162
	v_mov_b32_e32 v162, v195
	v_mov_b32_e32 v194, v167
	v_mov_b32_e32 v167, v163
	v_mov_b32_e32 v163, v194
	s_mov_b32 s100, 1
	v_lshlrev_b32_e32 v190, 16, v180
	v_and_b32_e32 v191, 0xffff0000, v180
	v_lshlrev_b32_e32 v180, 16, v181
	v_and_b32_e32 v181, 0xffff0000, v181
	v_pk_add_f32 v[128:129], v[128:129], v[180:181]
	v_pk_add_f32 v[126:127], v[126:127], v[190:191]
	v_mul_f32_e32 v181, v129, v129
	v_mul_f32_e32 v180, v127, v127
	v_fmac_f32_e32 v180, v126, v126
	v_fmac_f32_e32 v181, v128, v128
	v_cvt_pk_bf16_f32 v126, v126, v127
	v_cvt_pk_bf16_f32 v127, v128, v129
	v_lshl_add_u64 v[128:129], s[42:43], 0, v[178:179]
	v_lshl_add_u64 v[128:129], v[128:129], 0, v[176:177]
	v_lshl_add_u64 v[128:129], v[128:129], 0, v[200:201]
	v_mov_b32_e32 v192, v126
	v_mov_b32_e32 v193, v127
	v_lshlrev_b32_e32 v126, 16, v182
	v_and_b32_e32 v127, 0xffff0000, v182
	v_pk_add_f32 v[122:123], v[122:123], v[126:127]
	v_lshlrev_b32_e32 v176, 16, v183
	v_and_b32_e32 v177, 0xffff0000, v183
	v_mul_f32_e32 v126, v123, v123
	v_pk_add_f32 v[124:125], v[124:125], v[176:177]
	v_fmac_f32_e32 v126, v122, v122
	v_cvt_pk_bf16_f32 v122, v122, v123
	v_cvt_pk_bf16_f32 v123, v124, v125
	v_mul_f32_e32 v127, v125, v125
	v_mov_b32_e32 v194, v122
	v_mov_b32_e32 v195, v123
	s_nop 1
	v_permlane16_swap_b32_e32 v192, v194
	v_permlane16_swap_b32_e32 v193, v195
	global_store_dwordx4 v[128:129], v[192:195], off
	v_lshlrev_b32_e32 v122, 16, v184
	v_and_b32_e32 v123, 0xffff0000, v184
	v_fmac_f32_e32 v127, v124, v124
	v_lshlrev_b32_e32 v124, 16, v185
	v_and_b32_e32 v125, 0xffff0000, v185
	v_pk_add_f32 v[118:119], v[118:119], v[122:123]
	v_pk_add_f32 v[120:121], v[120:121], v[124:125]
	v_mul_f32_e32 v122, v119, v119
	v_fmac_f32_e32 v122, v118, v118
	v_mul_f32_e32 v123, v121, v121
	v_cvt_pk_bf16_f32 v118, v118, v119
	v_cvt_pk_bf16_f32 v119, v120, v121
	v_fmac_f32_e32 v123, v120, v120
	v_mov_b32_e32 v196, v118
	v_mov_b32_e32 v197, v119
	v_lshlrev_b32_e32 v118, 16, v188
	v_and_b32_e32 v119, 0xffff0000, v188
	v_lshlrev_b32_e32 v120, 16, v189
	v_and_b32_e32 v121, 0xffff0000, v189
	v_pk_add_f32 v[116:117], v[116:117], v[120:121]
	v_pk_add_f32 v[118:119], v[114:115], v[118:119]
	v_add_f32_e32 v180, v180, v181
	v_add_f32_e32 v126, v126, v127
	v_mul_f32_e32 v114, v119, v119
	v_mul_f32_e32 v115, v117, v117
	v_add_f32_e32 v126, v180, v126
	v_add_f32_e32 v122, v122, v123
	v_fmac_f32_e32 v114, v118, v118
	v_fmac_f32_e32 v115, v116, v116
	v_add_f32_e32 v122, v126, v122
	v_add_f32_e32 v114, v114, v115
	v_cvt_pk_bf16_f32 v118, v118, v119
	v_cvt_pk_bf16_f32 v119, v116, v117
	v_and_b32_e32 v116, 64, v229
	v_add_f32_e32 v115, v122, v114
	v_xor_b32_e32 v114, 16, v229
	v_add_u32_e32 v117, 64, v116
	v_cmp_lt_i32_e32 vcc, v114, v117
	v_mov_b32_e32 v198, v118
	v_mov_b32_e32 v199, v119
	s_nop 1
	v_permlane16_swap_b32_e32 v196, v198
	v_permlane16_swap_b32_e32 v197, v199
	global_store_dwordx4 v[128:129], v[196:199], off offset:256
	s_nop 0
	v_cndmask_b32_e32 v114, v229, v114, vcc
	v_lshlrev_b32_e32 v114, 2, v114
	v_mov_b32_e32 v116, v115
	s_nop 1
	v_permlane16_swap_b32_e32 v116, v115
	s_waitcnt lgkmcnt(0)
	v_add_f32_e32 v116, v115, v116
	v_xor_b32_e32 v115, 32, v229
	v_cmp_lt_i32_e32 vcc, v115, v117
	s_nop 1
	v_cndmask_b32_e32 v115, v229, v115, vcc
	v_lshlrev_b32_e32 v115, 2, v115
	ds_bpermute_b32 v117, v115, v116
	s_and_saveexec_b64 s[74:75], s[4:5]
	s_cbranch_execz .LBB0_1517
	v_readlane_b32 s12, v253, 38
	v_lshlrev_b64 v[118:119], 6, v[140:141]
	v_readlane_b32 s13, v253, 39
	s_lshl_b32 s64, s82, 2
	s_waitcnt lgkmcnt(0)
	v_add_f32_e32 v116, v116, v117
	v_lshl_add_u64 v[118:119], s[12:13], 0, v[118:119]
	v_lshl_add_u64 v[118:119], s[72:73], 2, v[118:119]
	v_lshl_add_u64 v[118:119], v[118:119], 0, s[64:65]
	global_store_dword v[118:119], v116, off
